# P4 pass-0 reorder (LoRA item first on its wave, q/k rows on the other seven) with the later code padded back to its original 64-byte placement phase
# baseline (speedup 1.0000x reference)
.LBB0_900:
	v_readlane_b32 s0, v255, 60
	s_nop 0
	s_cmp_eq_u32 s0, 1
	s_cbranch_scc0 .Lp4_join
	s_mov_b32 s0, 2
	v_writelane_b32 v255, s0, 60
	v_lshlrev_b32_e32 v180, 4, v178
	s_branch .LBB0_796
	s_nop 0
	s_nop 0
	s_nop 0
	s_nop 0
	s_nop 0
	s_nop 0
	s_nop 0
